# phase0a item loop: the 7th item of wave 0 (one weight-transpose block) moved to wave 6 or 7 of the same workgroup so no wave has GEMV + 6 transposes
# baseline (speedup 1.0000x reference)
.LBB0_42:
	s_or_b64 exec, exec, s[0:1]
	s_mul_i32 s0, s39, s42
	v_writelane_b32 v252, s78, 4
	s_lshl_b32 s80, s42, 3
	s_add_i32 s18, s41, s0
	v_writelane_b32 v252, s79, 5
	s_cmpk_gt_i32 s18, 0x30ff
	v_writelane_b32 v252, s41, 6
	s_waitcnt lgkmcnt(0)
	s_barrier
	s_cbranch_scc1 .LBB0_64
	s_mul_i32 s0, s39, 0x2100
	s_lshl_b32 s101, s39, 8
	s_movk_i32 s100, 0x3100
	s_cmp_eq_u32 s39, 0
	s_cselect_b32 s100, 0x3000, s100
	s_and_b32 s4, s41, 1
	s_add_i32 s4, s4, 6
	s_cmp_eq_u32 s39, s4
	s_cselect_b32 s100, 0x3900, s100
	v_ashrrev_i32_e32 v34, 5, v6
	v_and_b32_e32 v0, 31, v6
	s_movk_i32 s4, 0x84
	s_add_i32 s0, s0, 0
	v_lshlrev_b32_e32 v1, 2, v0
	v_mul_lo_u32 v2, v34, s4
	s_add_u32 s19, s46, 0x100000
	v_add3_u32 v35, s0, v1, v2
	v_lshlrev_b32_e32 v1, 3, v6
	s_addc_u32 s20, s47, 0
	v_ashrrev_i32_e32 v36, 3, v6
	v_and_b32_e32 v2, 56, v1
	v_mul_u32_u24_e32 v1, 0x84, v2
	v_lshlrev_b32_e32 v3, 2, v36
	s_add_u32 s21, s46, 0x9c00000
	s_mov_b32 s1, 0
	v_mov_b32_e32 v25, 0
	v_add3_u32 v37, s0, v1, v3
	v_add_u32_e32 v38, 8, v36
	v_add_u32_e32 v39, 16, v36
	v_add_u32_e32 v40, 24, v36
	v_lshlrev_b32_e32 v41, 2, v6
	s_addc_u32 s22, s47, 0
	s_movk_i32 s23, 0x2000
	s_movk_i32 s24, 0x4000
	s_movk_i32 s25, 0x6000
	s_mov_b32 s26, 0x8000
	s_mov_b32 s27, 0xa000
	s_mov_b32 s28, 0xc000
	s_mov_b32 s29, 0xe000
	s_mov_b32 s30, 0x10000
	s_mov_b32 s31, 0x12000
	s_mov_b32 s34, 0x14000
	s_mov_b32 s35, 0x16000
	s_mov_b32 s36, 0x18000
	s_mov_b32 s37, 0x1a000
	s_mov_b32 s40, 0x1c000
	s_mov_b32 s41, 0x1e000
	s_mov_b32 s48, 0x20000
	s_mov_b32 s49, 0x22000
	s_mov_b32 s50, 0x24000
	s_mov_b32 s51, 0x26000
	s_mov_b32 s52, 0x28000
	s_mov_b32 s53, 0x2a000
	s_mov_b32 s54, 0x2c000
	s_mov_b32 s55, 0x2e000
	s_mov_b32 s56, 0x30000
	s_mov_b32 s57, 0x32000
	s_mov_b32 s58, 0x34000
	s_mov_b32 s59, 0x36000
	s_mov_b32 s60, 0x38000
	s_mov_b32 s61, 0x3a000
	s_mov_b32 s62, 0x3c000
	s_mov_b32 s63, 0x3e000
	s_mov_b64 s[4:5], 0x1000000
	s_movk_i32 s64, 0x1600
	s_movk_i32 s65, 0x5800
	s_mov_b64 s[6:7], 0x500000
	s_mov_b64 s[8:9], 0x300000
	s_movk_i32 s66, 0x1800
	s_mov_b64 s[10:11], 0x18000
	s_mov_b32 s67, 0xfffe8000
	s_mov_b32 s68, 0xfffee000
	s_mov_b32 s69, 0xffff4000
	s_movk_i32 s70, 0xa000
	s_mov_b64 s[12:13], 0x30000
	v_lshlrev_b32_e32 v24, 2, v0
	v_add_u32_e32 v42, 0x400, v35
	v_add_u32_e32 v43, 0x800, v35
	v_add_u32_e32 v44, 0xc00, v35
	v_add_u32_e32 v45, 0x1000, v35
	v_add_u32_e32 v46, 0x1400, v35
	v_add_u32_e32 v47, 0x1800, v35
	v_add_u32_e32 v48, 0x1c00, v35
	v_lshlrev_b32_e32 v26, 1, v2
	s_branch .LBB0_45
.LBB0_44:
	s_add_i32 s18, s18, s80
	s_cmp_lt_i32 s18, s100
	s_cbranch_scc0 .LBB0_63
.LBB0_45:
	s_cmpk_lt_i32 s18, 0x3100
	s_cbranch_scc1 .Lp0a_norm
	s_sub_i32 s18, s18, s101
	s_movk_i32 s100, 0x3100
